# P0 converts W1 (the first GEMM phase's weight) last instead of first, on top of v148
# baseline (speedup 1.0000x reference)
; #define SEG_GU(Wsrc, gainp, dst, half) if (r < I_GU) { const int nblk = FF / 64, kb = r / nblk, nb = r % nblk, n0 = 64 * nb; \
;                 p0_item(Wsrc, FF, n0, 64 * kb, gainp, dst, DM, (n0 / 128) * 256 + (n0 % 128) + (half) * 128, scr, lane); continue; } r -= I_GU;
; #define SEG_ID(Wsrc, ldw, colbase, Kdim, ncols, gainp, dst, drow, cnt) if (r < (cnt)) { const int nblk = (ncols) / 64, kb = r / nblk, nb = r % nblk; \
;                 p0_item(Wsrc, ldw, (colbase) + 64 * nb, 64 * kb, gainp, dst, Kdim, (drow) + 64 * nb, scr, lane); continue; } r -= (cnt);
; __global__ void __launch_bounds__(NWAVES * 64, 2) fwd_megakernel(Args args) {
;     ...
;         for (int it = gw; it < NITEMS; it += NGW) {
;             int r = it;
;     ...
;             SEG_GU(args.in[3], args.in[2], W1, 0)
;             SEG_GU(args.in[4], args.in[2], W1, 1)
;             SEG_ID(args.in[5], DM, 0, FF, DM, (const float*)nullptr, WD1, 0, I_DN)
;             SEG_ID(args.in[7], DIN, 0, DM, 1024, args.in[6], WQK, 0, I_IN)
;             SEG_ID(args.in[7], DIN, 1024, DM, 1024, args.in[6], WQK, 1024, I_IN)
;             SEG_ID(args.in[7], DIN, 2048, DM, 1024, args.in[6], WV, 0, I_IN)
;             SEG_ID(args.in[7], DIN, 3080, DM, 1024, args.in[6], WQK, 2048, I_IN)
;             SEG_ID(args.in[7], DIN, 4104, DM, 1024, args.in[6], WQK, 3072, I_IN)
;             SEG_ID(args.in[7], DIN, 5128, DM, 1024, args.in[6], WV, 1024, I_IN)
;             SEG_ID(args.in[9], DM, 0, DM, DM, (const float*)nullptr, WO, 0, I_SQ)
;             SEG_GU(args.in[11], args.in[10], W2, 0)
;             SEG_GU(args.in[12], args.in[10], W2, 1)
;             SEG_ID(args.in[13], DM, 0, FF, DM, (const float*)nullptr, WD2, 0, I_DN)
;             SEG_ID(args.in[15], DM, 0, DM, DM, args.in[14], WPG, 0, I_SQ)
;             SEG_ID(args.in[16], DM, 0, PLE, DM, (const float*)nullptr, WPP, 0, I_PP)
.Lp0_loop:
	s_mov_b32 s3, s55
	s_cmpk_lt_u32 s3, 0xb00
	s_cbranch_scc1 .Lp0_seg0
	s_sub_u32 s3, s3, 0xb00
	s_cmpk_lt_u32 s3, 0x200
	s_cbranch_scc1 .Lp0_seg1
	s_sub_u32 s3, s3, 0x200
	s_cmpk_lt_u32 s3, 0x200
	s_cbranch_scc1 .Lp0_seg2
	s_sub_u32 s3, s3, 0x200
	s_cmpk_lt_u32 s3, 0x200
	s_cbranch_scc1 .Lp0_seg3
	s_sub_u32 s3, s3, 0x200
	s_cmpk_lt_u32 s3, 0x200
	s_cbranch_scc1 .Lp0_seg4
	s_sub_u32 s3, s3, 0x200
	s_cmpk_lt_u32 s3, 0x200
	s_cbranch_scc1 .Lp0_seg5
	s_sub_u32 s3, s3, 0x200
	s_cmpk_lt_u32 s3, 0x200
	s_cbranch_scc1 .Lp0_seg6
	s_sub_u32 s3, s3, 0x200
	s_cmpk_lt_u32 s3, 0x400
	s_cbranch_scc1 .Lp0_seg7
	s_sub_u32 s3, s3, 0x400
	s_cmpk_lt_u32 s3, 0xb00
	s_cbranch_scc1 .Lp0_seg8
	s_sub_u32 s3, s3, 0xb00
	s_cmpk_lt_u32 s3, 0xb00
	s_cbranch_scc1 .Lp0_seg9
	s_sub_u32 s3, s3, 0xb00
	s_cmpk_lt_u32 s3, 0xb00
	s_cbranch_scc1 .Lp0_seg10
	s_sub_u32 s3, s3, 0xb00
	s_cmpk_lt_u32 s3, 0x400
	s_cbranch_scc1 .Lp0_seg11
	s_sub_u32 s3, s3, 0x400
	s_cmpk_lt_u32 s3, 0x80
	s_cbranch_scc1 .Lp0_seg12
	s_sub_u32 s3, s3, 0x80
	s_cmpk_lt_u32 s3, 0xb00
	s_cbranch_scc1 .Lp0_seg13
	s_sub_u32 s3, s3, 0xb00
	s_branch .Lp0_seg14

; #define SEG_GU(Wsrc, gainp, dst, half) if (r < I_GU) { const int nblk = FF / 64, kb = r / nblk, nb = r % nblk, n0 = 64 * nb; \
;                 p0_item(Wsrc, FF, n0, 64 * kb, gainp, dst, DM, (n0 / 128) * 256 + (n0 % 128) + (half) * 128, scr, lane); continue; } r -= I_GU;
; __device__ __forceinline__ void p0_item(const float* W, int ldw, int col0, int k0, const float* gain, bf16_t* WT, int K, int drow0, LAS float* scr, int lane) {
;     ...
;     const int c = lane & 7;
;     f32x4 g0 = {1.f, 1.f, 1.f, 1.f}, g1 = {1.f, 1.f, 1.f, 1.f};
;     if (gain) { g0 = *(const f32x4*)(gain + k0 + 8 * c); g1 = *(const f32x4*)(gain + k0 + 8 * c + 4); }
; __global__ void __launch_bounds__(NWAVES * 64, 2) fwd_megakernel(Args args) {
;     ...
;             SEG_GU(args.in[3], args.in[2], W1, 0)
;             SEG_GU(args.in[4], args.in[2], W1, 1)
.Lp0_seg12:
	v_readlane_b32 s28, v250, 0
	v_readlane_b32 s29, v250, 1
	s_mov_b64 s[34:35], 0
	s_add_u32 s36, s60, 0xae00000
	s_addc_u32 s37, s61, 0
	s_lshr_b32 s4, s3, 5
	s_and_b32 s5, s3, 31
	s_lshl_b32 s33, s4, 6
	s_lshl_b32 s5, s5, 6
	s_mov_b32 s31, s5
	s_movk_i32 s30, 0x800
	s_movk_i32 s38, 0x100
	s_mov_b32 s39, s5
	s_branch .Lp0_item
.Lp0_seg13:
	s_mov_b64 s[28:29], s[14:15]
	s_mov_b64 s[34:35], s[12:13]
	s_add_u32 s36, s60, 0x200000
	s_addc_u32 s37, s61, 0
	s_mul_i32 s4, s3, 0xba3
	s_lshr_b32 s4, s4, 18
	s_mul_i32 s5, s4, 88
	s_sub_u32 s5, s3, s5
	s_lshl_b32 s33, s4, 6
	s_lshl_b32 s31, s5, 6
	s_movk_i32 s30, 0x1600
	s_movk_i32 s38, 0x800
	s_lshr_b32 s6, s5, 1
	s_lshl_b32 s6, s6, 8
	s_and_b32 s7, s5, 1
	s_lshl_b32 s7, s7, 6
	s_add_u32 s39, s6, s7
	s_branch .Lp0_item
.Lp0_seg14:
	s_mov_b64 s[28:29], s[16:17]
	s_mov_b64 s[34:35], s[12:13]
	s_add_u32 s36, s60, 0x200000
	s_addc_u32 s37, s61, 0
	s_mul_i32 s4, s3, 0xba3
	s_lshr_b32 s4, s4, 18
	s_mul_i32 s5, s4, 88
	s_sub_u32 s5, s3, s5
	s_lshl_b32 s33, s4, 6
	s_lshl_b32 s31, s5, 6
	s_movk_i32 s30, 0x1600
	s_movk_i32 s38, 0x800
	s_lshr_b32 s6, s5, 1
	s_lshl_b32 s6, s6, 8
	s_and_b32 s7, s5, 1
	s_lshl_b32 s7, s7, 6
	s_add_u32 s39, s6, s7
	s_add_u32 s39, s39, 0x80
	s_branch .Lp0_item
.Lp0_item:
	s_cmp_eq_u64 s[34:35], 0
	s_cbranch_scc1 .Lp0_nogain
	s_lshl_b32 s4, s33, 2
	s_add_u32 s42, s34, s4
	s_addc_u32 s43, s35, 0
	global_load_dwordx4 v[68:71], v67, s[42:43]
	global_load_dwordx4 v[72:75], v67, s[42:43] offset:16
	s_branch .Lp0_rows
